# v68: the post-UP invalidate of workgroups 0..63 is also issued at arrival (overlaps the barrier wait) like the other acquires
# baseline (speedup 1.0000x reference)
; __device__ __forceinline__ unsigned xb_ld(unsigned* p)              { return __hip_atomic_load(p, __ATOMIC_RELAXED, __HIP_MEMORY_SCOPE_AGENT); }
; __device__ __forceinline__ unsigned xb_add(unsigned* p, unsigned v) { return __hip_atomic_fetch_add(p, v, __ATOMIC_RELAXED, __HIP_MEMORY_SCOPE_AGENT); }
; #define XB_SPIN(cond, bar) do { unsigned _sp = 0; while (cond) { __builtin_amdgcn_s_sleep(1); \
;     if ((++_sp & 255u) == 0u) { if (xb_ld(&(bar)[XB_TMO])) break; if (_sp > XB_SPIN_CAP) { atomicAdd(&(bar)[XB_TMO], 1u); break; } } } } while (0)
; __device__ __forceinline__ void xcd_barrier(const XcdBarrier& b) {
;     ...
;     if (threadIdx.x == 0) {
;         unsigned* bar = b.bar;
;         __builtin_amdgcn_s_waitcnt(0);
;         unsigned nloc = b.st[0], nx = b.st[1];
;         if (nloc == 0u) { xcd_barrier_complete(bar, b.x, nloc, nx); b.st[0] = nloc; b.st[1] = nx; }
;         const unsigned old = xb_add(&bar[XB_XSUB(b.x)], 1u);
;         const unsigned gen = old / nloc;
;         if (old + 1u == (gen + 1u) * nloc) {
;             __builtin_amdgcn_fence(__ATOMIC_RELEASE, "agent");
;             asm volatile("s_waitcnt vmcnt(0)" ::: "memory");
;             const unsigned og = xb_add(&bar[XB_TOP], 1u);
;             const unsigned tg = og / nx;
;             if (og + 1u == (tg + 1u) * nx) xb_add(&bar[XB_TOPGEN], 1u);
;             else XB_SPIN(xb_ld(&bar[XB_TOPGEN]) == tg, bar);
;             __builtin_amdgcn_fence(__ATOMIC_ACQUIRE, "agent");
;             xb_add(&bar[XB_XGEN(b.x)], 1u);
;             asm volatile("s_waitcnt vmcnt(0)" ::: "memory");
;         } else {
;             XB_SPIN(xb_ld(&bar[XB_XGEN(b.x)]) == gen, bar);
;             __builtin_amdgcn_fence(__ATOMIC_ACQUIRE, "agent");
;             asm volatile("s_waitcnt vmcnt(0)" ::: "memory");
;         }
.LBB0_1119:
	v_mov_b32_e32 v4, 0x20000
	ds_read2_b32 v[2:3], v4 offset1:1
	v_readlane_b32 s3, v244, 30
	s_nop 0
	s_lshl_b32 s3, s3, 8
	s_getpc_b64 s[8:9]
	s_add_u32 s8, s8, g_xbar@rel32@lo+4
	s_addc_u32 s9, s9, g_xbar@rel32@hi+12
	s_add_u32 s8, s8, s3
	s_addc_u32 s9, s9, 0
	v_mov_b32_e32 v5, 0x1000
	v_mov_b32_e32 v6, 1
	global_atomic_add v5, v5, v6, s[8:9] offset:1024 sc0
	s_movk_i32 s3, 8
	s_waitcnt lgkmcnt(0)
	v_mul_lo_u32 v2, v2, s3
	v_mul_lo_u32 v3, v3, s3
	s_waitcnt vmcnt(0)
	s_cmp_lg_u32 s33, 0x100
	s_cbranch_scc1 .Lfb7_doinv
	v_readlane_b32 s3, v244, 33
	s_nop 3
	s_cmp_lt_u32 s3, 64
	s_cbranch_scc0 .Lfb7_noinv

; __device__ __forceinline__ unsigned xb_add(unsigned* p, unsigned v) { return __hip_atomic_fetch_add(p, v, __ATOMIC_RELAXED, __HIP_MEMORY_SCOPE_AGENT); }
; __device__ __forceinline__ void xcd_barrier(const XcdBarrier& b) {
;     ...
;         if (old + 1u == (gen + 1u) * nloc) {
;             __builtin_amdgcn_fence(__ATOMIC_RELEASE, "agent");
;             asm volatile("s_waitcnt vmcnt(0)" ::: "memory");
;             const unsigned og = xb_add(&bar[XB_TOP], 1u);
;             const unsigned tg = og / nx;
;             if (og + 1u == (tg + 1u) * nx) xb_add(&bar[XB_TOPGEN], 1u);
.Lfb7_noinv:
	v_add_u32_e32 v5, 1, v5
	v_cmp_ne_u32_e32 vcc, v5, v2
	s_getpc_b64 s[8:9]
	s_add_u32 s8, s8, g_xbar@rel32@lo+13316
	s_addc_u32 s9, s9, g_xbar@rel32@hi+13324
	v_mov_b32_e32 v4, 0
	s_cbranch_vccnz .Lfb7_spin0
	buffer_wbl2 sc1
	s_waitcnt vmcnt(0) lgkmcnt(0)
	global_atomic_add v4, v6, s[8:9]
